# grid barrier: barrier generation kept in an LDS word, so the two u32 divisions on the arrive / top-level paths become one multiply-add each
# baseline (speedup 1.0000x reference)
; DI unsigned xb_add(unsigned* p, unsigned v) { return __hip_atomic_fetch_add(p, v, __ATOMIC_RELAXED, __HIP_MEMORY_SCOPE_AGENT); }
; DI void xcd_barrier(const XcdBarrier& b) {
;     ...
;     unsigned nloc = b.st[0], nx = b.st[1];
;     if (nloc == 0u) { xcd_barrier_complete(bar, b.x, nloc, nx); b.st[0] = nloc; b.st[1] = nx; }
;     const unsigned old = xb_add(&bar[XB_XSUB(b.x)], 1u);
;     const unsigned gen = old / nloc;
;     if (old + 1u == (gen + 1u) * nloc) {
.LBB0_2088:
	ds_read_b32 v7, v163 offset:8
	s_mov_b64 s[6:7], exec
	v_mbcnt_lo_u32_b32 v0, s6, 0
	v_mbcnt_hi_u32_b32 v0, s7, v0
	v_cmp_eq_u32_e32 vcc, 0, v0
	s_and_saveexec_b64 s[4:5], vcc
	s_cbranch_execz .LBB0_2090
	s_bcnt1_i32_b64 s6, s[6:7]
	v_mov_b32_e32 v4, s6
	v_readlane_b32 s6, v238, 17
	v_readlane_b32 s7, v238, 18
	s_nop 4
	global_atomic_add v4, v1, v4, s[6:7] sc0
.LBB0_2090:
	s_or_b64 exec, exec, s[4:5]
	s_waitcnt vmcnt(0) lgkmcnt(0)
	v_readfirstlane_b32 s4, v4
	v_add_u32_e32 v6, s4, v0
	v_mov_b32_e32 v0, v7
	v_mul_lo_u32 v5, v3, v0
	v_add_u32_e32 v8, 1, v7
	v_add_u32_e32 v4, 1, v6
	v_add_u32_e32 v3, v5, v3
	ds_write_b32 v163, v8 offset:8
	v_cmp_ne_u32_e32 vcc, v4, v3
	s_and_saveexec_b64 s[4:5], vcc
	s_xor_b64 s[4:5], exec, s[4:5]
	s_cbranch_execz .LBB0_2104
	buffer_inv sc1
	v_readlane_b32 s6, v238, 19
	v_readlane_b32 s7, v238, 20
	s_waitcnt lgkmcnt(0)
	s_nop 3
	global_load_dword v2, v1, s[6:7] sc1
	s_waitcnt vmcnt(0)
	v_cmp_eq_u32_e32 vcc, v2, v0
	s_and_saveexec_b64 s[6:7], vcc
	s_cbranch_execz .LBB0_2103
	s_mov_b32 s18, 1
	s_mov_b64 s[8:9], 0
	s_branch .LBB0_2094

; DI unsigned xb_ld(unsigned* p) { return __hip_atomic_load(p, __ATOMIC_RELAXED, __HIP_MEMORY_SCOPE_AGENT); }
; DI unsigned xb_add(unsigned* p, unsigned v) { return __hip_atomic_fetch_add(p, v, __ATOMIC_RELAXED, __HIP_MEMORY_SCOPE_AGENT); }
; #define XB_SPIN(cond, bar) do { unsigned _sp = 0; while (cond) { __builtin_amdgcn_s_sleep(1); \
;     if ((++_sp & 255u) == 0u) { if (xb_ld(&(bar)[XB_TMO])) break; if (_sp > XB_SPIN_CAP) { atomicAdd(&(bar)[XB_TMO], 1u); break; } } } } while (0)
; DI void xcd_barrier(const XcdBarrier& b) {
;     ...
;       const unsigned og = xb_add(&bar[XB_TOP], 1u);
;       const unsigned tg = og / nx;
;       if (og + 1u == (tg + 1u) * nx) xb_add(&bar[XB_TOPGEN], 1u);
;       else XB_SPIN(xb_ld(&bar[XB_TOPGEN]) == tg, bar);
.LBB0_2107:
	s_or_b64 exec, exec, s[6:7]
	s_waitcnt vmcnt(0)
	v_readfirstlane_b32 s4, v3
	s_mov_b64 s[6:7], -1
	v_add_u32_e32 v3, s4, v0
	v_readlane_b32 s4, v238, 23
	v_readlane_b32 s5, v238, 24
	v_mov_b32_e32 v0, v7
	v_add_u32_e32 v3, 1, v3
	v_mul_lo_u32 v4, v2, v0
	v_add_u32_e32 v2, v4, v2
	v_cmp_ne_u32_e32 vcc, v3, v2
	v_mov_b64_e32 v[2:3], s[4:5]
	s_and_saveexec_b64 s[4:5], vcc
	s_cbranch_execz .LBB0_2119
	v_readlane_b32 s6, v238, 23
	v_readlane_b32 s7, v238, 24
	s_mov_b64 s[8:9], 0
	s_nop 3
	global_load_dword v2, v1, s[6:7] sc1
	s_waitcnt vmcnt(0)
	v_cmp_eq_u32_e32 vcc, v2, v0
	s_and_saveexec_b64 s[6:7], vcc
	s_cbranch_execz .LBB0_2118
	s_mov_b32 s18, 1
	s_branch .LBB0_2111
